# o24 + 6 weight-conversion filler pulls per idle workgroup moved from the MIX1 queue tail into WIN's idle last round (own counter), combined with the LPT queue order
# speedup vs baseline: 1.0162x; 1.0039x over previous
.LBB0_1169:
	s_waitcnt vmcnt(0)
	v_readlane_b32 s80, v254, 8
	v_readlane_b32 s81, v254, 9
	v_readlane_b32 s82, v254, 10
	v_readlane_b32 s83, v254, 11
	v_readlane_b32 s84, v254, 12
	v_readlane_b32 s85, v254, 13
	v_readlane_b32 s86, v254, 14
	v_readlane_b32 s87, v254, 15
	s_barrier
	v_readlane_b32 s101, v253, 0
	s_nop 3
	s_cmpk_lt_u32 s101, 0x61
	s_cbranch_scc1 .LBB0_1170
	s_mov_b32 s99, 1
	s_movk_i32 s98, 0x410
	s_movk_i32 s100, 0x7
	s_add_u32 s0, s86, 0xc800
	s_addc_u32 s1, s87, 0
	v_writelane_b32 v254, s0, 22
	v_mov_b32_e32 v1, v0
	s_branch .Lmix1_entry

.LBB0_1222:
	s_or_b64 exec, exec, s[0:1]
	s_mov_b32 s99, 0
	s_mov_b32 s98, 0
	s_add_u32 s0, s86, 0xc200
	s_addc_u32 s1, s87, 0
	v_writelane_b32 v254, s0, 22
	s_waitcnt lgkmcnt(0)
	v_mov_b32_e32 v1, v0
	s_barrier

.LBB0_1229:
	s_or_b64 exec, exec, s[0:1]
	s_waitcnt lgkmcnt(0)
	s_barrier
	ds_read_b32 v1, v155
	s_movk_i32 s0, 0x8af
	s_waitcnt lgkmcnt(0)
	v_add_u32_e32 v1, s98, v1
	v_cmp_lt_u32_e32 vcc, s0, v1
	v_readfirstlane_b32 s42, v1
	s_mov_b64 s[0:1], -1
	s_cbranch_vccnz .LBB0_1224
	s_cmpk_gt_u32 s42, 0x2ff
	s_cbranch_scc1 .Lq_nomap
	s_cmpk_lt_u32 s42, 0x80
	s_cbranch_scc1 .Lq_nomap
	s_cmpk_lt_u32 s42, 0x280
	s_cbranch_scc1 .Lq_g1
	s_sub_u32 s42, s42, 0x200
	s_branch .Lq_nomap

.Lq_nomap:
	s_cmpk_gt_u32 s42, 0xff
	s_cbranch_scc0 .LBB0_1402
	s_cmpk_gt_u32 s42, 0x2ff
	s_cbranch_scc0 .LBB0_1300
	s_cmpk_gt_u32 s42, 0x407
	s_cbranch_scc0 .LBB0_1274
	s_cmpk_gt_u32 s42, 0x40f
	s_cbranch_scc0 .LBB0_1271
	s_cmp_lg_u32 s98, 0
	s_cbranch_scc1 .Lfill_go
	s_movk_i32 s98, 0x410
	s_add_u32 s0, s86, 0xc800
	s_addc_u32 s1, s87, 0
	v_writelane_b32 v254, s0, 22
	s_nop 0
	v_writelane_b32 v254, s1, 23
	s_branch .LBB0_1225
